# layer-0 w_in GEMM: per XCD round 4 row tiles x 8 column tiles instead of 8 x 4 (same 6-position stagger)
# speedup vs baseline: 1.0014x; 1.0014x over previous
.Lgi_sk_rot0:
	s_and_b32 s0, s54, 7
	s_lshr_b32 s1, s54, 3
	s_mul_i32 s57, s0, 186
	s_add_u32 s1, s1, s57
	s_mul_i32 s57, s1, 0x5556
	s_lshr_b32 s57, s57, 22
	s_mul_i32 s57, s57, 192
	s_sub_u32 s1, s1, s57
	s_lshr_b32 s57, s1, 5
	s_and_b32 s1, s1, 31
	s_and_b32 vcc_lo, s57, 1
	s_lshl_b32 vcc_lo, vcc_lo, 2
	s_and_b32 vcc_hi, s1, 3
	s_add_u32 vcc_lo, vcc_lo, vcc_hi
	s_lshr_b32 s57, s57, 1
	s_lshl_b32 s57, s57, 3
	s_lshr_b32 s1, s1, 2
	s_add_u32 s1, s1, s57
	s_lshl_b32 s1, s1, 3
	s_add_u32 s1, s1, vcc_lo
	s_lshl_b32 s1, s1, 3
	s_or_b32 s57, s1, s0
	s_branch .Lgi_sk_dec
